# XCD-local polling for barriers 6,12,13 (census-guarded)
# baseline (speedup 1.0000x reference)
.LBB0_20:
	s_cmp_le_i32 s74, s36
	s_cbranch_scc1 .LBB0_74
	s_sub_u32 s37, s74, s36
	s_waitcnt vmcnt(0)
	s_barrier
	v_readfirstlane_b32 s0, v228
	s_nop 3
	s_cmp_lt_u32 s0, 64
	s_cbranch_scc0 .Lxb_join
	s_mov_b64 s[0:1], exec
	s_mov_b64 exec, 1
	ds_read_b32 v2, v208
	ds_read_b32 v0, v209
	ds_read_b32 v4, v208 offset:8
	s_waitcnt lgkmcnt(0)
	v_readfirstlane_b32 s2, v2
	v_readfirstlane_b32 s3, v0
	v_readfirstlane_b32 s36, v4
	s_nop 3
	s_cmp_lg_u32 s2, 0
	s_cbranch_scc1 .Lxb_have_census
	s_mov_b64 exec, 0xffff
	v_lshlrev_b32_e32 v4, 8, v237
	v_add_u32_e32 v4, 0x400, v4
	s_mov_b32 s39, 0

.Lxb_have_census:
	v_readlane_b32 s28, v253, 61
	v_readlane_b32 s29, v253, 62
	v_readlane_b32 s38, v254, 1
	v_readlane_b32 s39, v254, 2
	v_mov_b32_e32 v3, 1
	s_mul_i32 s2, s2, s37
	s_mul_i32 s3, s3, s37
	s_nop 4
	global_atomic_add v3, v201, v3, s[28:29] sc0
	buffer_inv sc1
	s_waitcnt vmcnt(0)
	v_readfirstlane_b32 s28, v3
	s_nop 3
	s_add_u32 s28, s28, 1
	s_cmp_eq_u32 s28, s2
	s_cbranch_scc0 .Lxb_poll
	s_cmp_eq_u32 s36, 1
	s_cbranch_scc0 .Lxb_flush
	s_cmp_eq_u32 s74, 6
	s_cbranch_scc1 .Lxb_last_local
	s_cmp_eq_u32 s74, 12
	s_cbranch_scc1 .Lxb_last_local
	s_cmp_eq_u32 s74, 13
	s_cbranch_scc1 .Lxb_last_local
	s_cmp_eq_u32 s74, 7
	s_cbranch_scc1 .Lxb_noflush
	s_cmp_eq_u32 s74, 8
	s_cbranch_scc1 .Lxb_noflush

.Lxb_noflush:
	global_atomic_add v201, v249, s[38:39]
	s_branch .Lxb_pollg

.Lxb_poll:
	s_cmp_eq_u32 s36, 1
	s_cbranch_scc0 .Lxb_pollg
	s_cmp_eq_u32 s74, 6
	s_cbranch_scc1 .Lxb_polll
	s_cmp_eq_u32 s74, 12
	s_cbranch_scc1 .Lxb_polll
	s_cmp_eq_u32 s74, 13
	s_cbranch_scc1 .Lxb_polll

.Lxb_poll_loop:
	global_load_dword v0, v201, s[38:39] sc1
	s_waitcnt vmcnt(0)
	v_readfirstlane_b32 s28, v0
	s_nop 3
	s_cmp_ge_u32 s28, s3
	s_cbranch_scc1 .Lxb_done
	s_sleep 1
	s_add_u32 s29, s29, 1
	s_cmp_lt_u32 s29, 0x4000
	s_cbranch_scc1 .Lxb_poll_loop
	s_branch .Lxb_done
.Lxb_polll:
	s_mov_b32 s29, 0
	v_readlane_b32 s38, v253, 61
	v_readlane_b32 s39, v253, 62
	s_nop 4
.Lxb_polll_loop:
	global_load_dword v0, v201, s[38:39] sc1
	s_waitcnt vmcnt(0)
	v_readfirstlane_b32 s28, v0
	s_nop 3
	s_cmp_ge_u32 s28, s2
	s_cbranch_scc1 .Lxb_done
	s_sleep 1
	s_add_u32 s29, s29, 1
	s_cmp_lt_u32 s29, 0x4000
	s_cbranch_scc1 .Lxb_polll_loop
